# fix: rare-path rescale of the matrix-pipe row-sum now uses the factor of query n+16 for accumulator reg1 (verified with a forced-rescale build); otherwise same as previous
# baseline (speedup 1.0000x reference)
; #define MFMA(a, b, c) __builtin_amdgcn_mfma_f32_32x32x16_bf16((a), (b), (c), 0, 0, 0)
; template <int DQK, bool BAND, int QT> ...
;     ...
;       f32x16 s[2][QT];
; #pragma unroll
;       for (int a = 0; a < 2; ++a)
; #pragma unroll
;         for (int b = 0; b < QT; ++b)
; #pragma unroll
;           for (int r = 0; r < 16; ++r) s[a][b][r] = 0.f;
; #pragma unroll
;       for (int ks = 0; ks < NKS; ++ks) {
;         const bf16x8 k0 = *(const bf16x8*)(st + k_rd + ks * 32);
;         const bf16x8 k1 = *(const bf16x8*)(st + k_rd + 32 * KROW + ks * 32);
; #pragma unroll
;         for (int qt = 0; qt < QT; ++qt) {
;           s[0][qt] = MFMA(k0, qf[qt][ks], s[0][qt]);
;           s[1][qt] = MFMA(k1, qf[qt][ks], s[1][qt]);
;         }
;       }
;       __builtin_amdgcn_s_setprio(3);
;       bf16x8 pf[QT][4];
;       const float cc = BAND ? 1.0f : scale_log2;
;       const float th = BAND ? 8.0f : 8.0f / scale_log2;
; #pragma unroll
;       for (int qt = 0; qt < QT; ++qt) {
;         if (BAND) {
; #pragma unroll
;           for (int a = 0; a < 2; ++a)
; #pragma unroll
;             for (int r = 0; r < 16; ++r) {
;               const int kidx = kt + 32 * a + (r & 7) + 8 * h + 16 * (r >> 3);
;               const int rel = kidx - (qw0 + qt * 32 + ql);
;               const bool ok = (rel >= -64) && (rel <= 64);
;               const int bi = ok ? rel + 64 : 0;
;               s[a][qt][r] = ok ? fmaf(s[a][qt][r], scale_log2, bias_l[bi]) : -1e30f;
;             }
;         }
;         float mx = s[0][qt][0];
; #pragma unroll
;         for (int r = 1; r < 16; ++r) mx = fmaxf(mx, s[0][qt][r]);
; #pragma unroll
;         for (int r = 0; r < 16; ++r) mx = fmaxf(mx, s[1][qt][r]);
;         mx = fmaxf(mx, __shfl_xor(mx, 32));
;         if (__builtin_amdgcn_ballot_w64(mx > m[qt] + th) != 0) {
;           const float mn = fmaxf(m[qt], mx);
;           const float alpha = __builtin_amdgcn_exp2f((m[qt] - mn) * cc);
;           m[qt] = mn;
;           l[qt] *= alpha;
; #pragma unroll
;           for (int r = 0; r < 16; ++r) { o[0][qt][r] *= alpha; o[1][qt][r] *= alpha; }
;         }
.Lgqa_top:
	ds_read_b128 v[206:209], v185
	ds_read_b128 v[210:213], v185 offset:4608
	ds_read_b128 v[214:217], v185 offset:32
	ds_read_b128 v[232:235], v185 offset:4640
	s_waitcnt lgkmcnt(3)
	v_mfma_f32_32x32x16_bf16 v[82:97], v[206:209], v[146:149], 0
	v_mfma_f32_32x32x16_bf16 v[114:129], v[206:209], v[162:165], 0
	ds_read_b128 v[206:209], v185 offset:64
	s_waitcnt lgkmcnt(3)
	v_mfma_f32_32x32x16_bf16 v[66:81], v[210:213], v[146:149], 0
	v_mfma_f32_32x32x16_bf16 v[98:113], v[210:213], v[162:165], 0
	ds_read_b128 v[210:213], v185 offset:4672
	s_waitcnt lgkmcnt(3)
	v_mfma_f32_32x32x16_bf16 v[82:97], v[214:217], v[150:153], v[82:97]
	v_mfma_f32_32x32x16_bf16 v[114:129], v[214:217], v[166:169], v[114:129]
	ds_read_b128 v[214:217], v185 offset:96
	s_waitcnt lgkmcnt(3)
	v_mfma_f32_32x32x16_bf16 v[66:81], v[232:235], v[150:153], v[66:81]
	v_mfma_f32_32x32x16_bf16 v[98:113], v[232:235], v[166:169], v[98:113]
	ds_read_b128 v[232:235], v185 offset:4704
	s_waitcnt lgkmcnt(3)
	v_mfma_f32_32x32x16_bf16 v[82:97], v[206:209], v[154:157], v[82:97]
	v_mfma_f32_32x32x16_bf16 v[114:129], v[206:209], v[170:173], v[114:129]
	s_waitcnt lgkmcnt(2)
	v_mfma_f32_32x32x16_bf16 v[66:81], v[210:213], v[154:157], v[66:81]
	v_mfma_f32_32x32x16_bf16 v[98:113], v[210:213], v[170:173], v[98:113]
	s_waitcnt lgkmcnt(1)
	v_mfma_f32_32x32x16_bf16 v[82:97], v[214:217], v[158:161], v[82:97]
	v_mfma_f32_32x32x16_bf16 v[114:129], v[214:217], v[174:177], v[114:129]
	s_waitcnt lgkmcnt(0)
	v_mfma_f32_32x32x16_bf16 v[66:81], v[232:235], v[158:161], v[66:81]
	v_mfma_f32_32x32x16_bf16 v[98:113], v[232:235], v[174:177], v[98:113]
	s_waitcnt vmcnt(0)
	s_nop 7
	s_setprio 0
	v_max_f32_e32 v203, v82, v83
	v_max_f32_e32 v253, v114, v115
	v_max3_f32 v203, v203, v84, v85
	v_max3_f32 v253, v253, v116, v117
	v_max3_f32 v203, v203, v86, v87
	v_max3_f32 v253, v253, v118, v119
	v_max3_f32 v203, v203, v88, v89
	v_max3_f32 v253, v253, v120, v121
	v_max3_f32 v203, v203, v90, v91
	v_max3_f32 v253, v253, v122, v123
	v_max3_f32 v203, v203, v92, v93
	v_max3_f32 v253, v253, v124, v125
	v_max3_f32 v203, v203, v94, v95
	v_max3_f32 v253, v253, v126, v127
	v_max3_f32 v203, v203, v96, v97
	v_max3_f32 v253, v253, v128, v129
	v_max3_f32 v203, v203, v66, v67
	v_max3_f32 v253, v253, v98, v99
	v_max3_f32 v203, v203, v68, v69
	v_max3_f32 v253, v253, v100, v101
	v_max3_f32 v203, v203, v70, v71
	v_max3_f32 v253, v253, v102, v103
	v_max3_f32 v203, v203, v72, v73
	v_max3_f32 v253, v253, v104, v105
	v_max3_f32 v203, v203, v74, v75
	v_max3_f32 v253, v253, v106, v107
	v_max3_f32 v203, v203, v76, v77
	v_max3_f32 v253, v253, v108, v109
	v_max3_f32 v203, v203, v78, v79
	v_max3_f32 v253, v253, v110, v111
	v_max3_f32 v203, v203, v80, v81
	v_max3_f32 v253, v253, v112, v113
	v_add_f32_e32 v254, 0x42317218, v197
	v_cmp_gt_f32_e32 vcc, v203, v254
	s_cbranch_vccz .Lgqa_nr0
	ds_bpermute_b32 v254, v179, v203
	s_waitcnt lgkmcnt(0)
	v_max_f32_e32 v254, v254, v254
	v_max_f32_e32 v203, v203, v254
	v_max_f32_e32 v254, v197, v197
	v_max_f32_e32 v203, v254, v203
	v_sub_f32_e32 v197, v197, v203
	v_mul_f32_e32 v197, 0x3e38aa3b, v197
	v_exp_f32_e32 v254, v197
	v_mov_b32_e32 v197, v203
	v_pk_mul_f32 v[64:65], v[64:65], v[254:255] op_sel_hi:[1,0]
	v_pk_mul_f32 v[62:63], v[62:63], v[254:255] op_sel_hi:[1,0]
	v_pk_mul_f32 v[60:61], v[60:61], v[254:255] op_sel_hi:[1,0]
	v_pk_mul_f32 v[58:59], v[58:59], v[254:255] op_sel_hi:[1,0]
	v_pk_mul_f32 v[56:57], v[56:57], v[254:255] op_sel_hi:[1,0]
	v_pk_mul_f32 v[54:55], v[54:55], v[254:255] op_sel_hi:[1,0]
	v_pk_mul_f32 v[52:53], v[52:53], v[254:255] op_sel_hi:[1,0]
	v_pk_mul_f32 v[50:51], v[50:51], v[254:255] op_sel_hi:[1,0]
	v_pk_mul_f32 v[48:49], v[48:49], v[254:255] op_sel_hi:[1,0]
	v_pk_mul_f32 v[46:47], v[46:47], v[254:255] op_sel_hi:[1,0]
	v_pk_mul_f32 v[44:45], v[44:45], v[254:255] op_sel_hi:[1,0]
	v_pk_mul_f32 v[42:43], v[42:43], v[254:255] op_sel_hi:[1,0]
	v_pk_mul_f32 v[40:41], v[40:41], v[254:255] op_sel_hi:[1,0]
	v_pk_mul_f32 v[38:39], v[38:39], v[254:255] op_sel_hi:[1,0]
	v_pk_mul_f32 v[36:37], v[36:37], v[254:255] op_sel_hi:[1,0]
	v_pk_mul_f32 v[34:35], v[34:35], v[254:255] op_sel_hi:[1,0]
	v_mbcnt_lo_u32_b32 v255, -1, 0
	v_mbcnt_hi_u32_b32 v255, -1, v255
	v_add_u32_e32 v255, 16, v255
	v_lshlrev_b32_e32 v255, 2, v255
	ds_bpermute_b32 v255, v255, v254
	s_waitcnt lgkmcnt(0)
	v_mul_f32_e32 v240, v240, v254
	v_mul_f32_e32 v241, v241, v255
.Lgqa_nr0:
	v_add_f32_e32 v254, 0x42317218, v202
	v_cmp_gt_f32_e32 vcc, v253, v254
	s_cbranch_vccz .Lgqa_nr1
	ds_bpermute_b32 v254, v179, v253
	s_waitcnt lgkmcnt(0)
	v_max_f32_e32 v254, v254, v254
	v_max_f32_e32 v253, v253, v254
	v_max_f32_e32 v254, v202, v202
	v_max_f32_e32 v253, v254, v253
	v_sub_f32_e32 v202, v202, v253
	v_mul_f32_e32 v202, 0x3e38aa3b, v202
	v_exp_f32_e32 v254, v202
	v_mov_b32_e32 v202, v253
	v_pk_mul_f32 v[32:33], v[32:33], v[254:255] op_sel_hi:[1,0]
	v_pk_mul_f32 v[30:31], v[30:31], v[254:255] op_sel_hi:[1,0]
	v_pk_mul_f32 v[28:29], v[28:29], v[254:255] op_sel_hi:[1,0]
	v_pk_mul_f32 v[26:27], v[26:27], v[254:255] op_sel_hi:[1,0]
	v_pk_mul_f32 v[24:25], v[24:25], v[254:255] op_sel_hi:[1,0]
	v_pk_mul_f32 v[22:23], v[22:23], v[254:255] op_sel_hi:[1,0]
	v_pk_mul_f32 v[20:21], v[20:21], v[254:255] op_sel_hi:[1,0]
	v_pk_mul_f32 v[18:19], v[18:19], v[254:255] op_sel_hi:[1,0]
	v_pk_mul_f32 v[16:17], v[16:17], v[254:255] op_sel_hi:[1,0]
	v_pk_mul_f32 v[14:15], v[14:15], v[254:255] op_sel_hi:[1,0]
	v_pk_mul_f32 v[12:13], v[12:13], v[254:255] op_sel_hi:[1,0]
	v_pk_mul_f32 v[10:11], v[10:11], v[254:255] op_sel_hi:[1,0]
	v_pk_mul_f32 v[8:9], v[8:9], v[254:255] op_sel_hi:[1,0]
	v_pk_mul_f32 v[6:7], v[6:7], v[254:255] op_sel_hi:[1,0]
	v_pk_mul_f32 v[4:5], v[4:5], v[254:255] op_sel_hi:[1,0]
	v_pk_mul_f32 v[2:3], v[2:3], v[254:255] op_sel_hi:[1,0]
	v_mbcnt_lo_u32_b32 v255, -1, 0
	v_mbcnt_hi_u32_b32 v255, -1, v255
	v_add_u32_e32 v255, 16, v255
	v_lshlrev_b32_e32 v255, 2, v255
	ds_bpermute_b32 v255, v255, v254
	s_waitcnt lgkmcnt(0)
	v_mul_f32_e32 v236, v236, v254
	v_mul_f32_e32 v237, v237, v255
